# sample RWKV step (P7): the 4 state-row loads of each unrolled group issued together with vmcnt(3) waits, instead of load / vmcnt(0) / store per row
# speedup vs baseline: 1.0121x; 1.0007x over previous
; __device__ __forceinline__ bf16_t f2bf(float f) { return (bf16_t)(cvt_pk_bf16(f, 0.f) & 0xffffu); }
; __device__ __forceinline__ float dot4(f32x4 a, f32x4 b) { return (a.x * b.x + a.y * b.y) + (a.z * b.z + a.w * b.w); }
; template <int ph>
; __device__ __forceinline__ void run_phase(const Args& args, LAS unsigned char* lds, const int G, const int bx, const bool fin = true) {
;     ...
; #pragma unroll 4
;                 for (int rg = 0; rg < 16; ++rg) {
;                     const int srow = 4 * rg + (lane >> 4);
;                     f32x4 S = *(const f32x4*)(state_rwkv + sbase + srow * 64 + 4 * cgq);
;                     const float vv = V1[320 + srow];
;                     const float sa = red16(dot4(S, nk)), z = red16(dot4(S, wrv));
;                     const float y = z + sa * br + vv * kr;
;                     S = S * w + bv * sa + kp * vv;
;                     *(f32x4*)(out + O_SRWKV + sbase + srow * 64 + 4 * cgq) = S;
;                     if (cgq == 0) Y[row * D + h * 64 + srow] = f2bf(y);
;                 }
.LBB0_1033:
	v_lshl_add_u64 v[40:41], v[32:33], 0, s[0:1]
	global_load_dwordx4 v[54:57], v[40:41], off
	global_load_dwordx4 v[90:93], v[40:41], off offset:1024
	global_load_dwordx4 v[94:97], v[40:41], off offset:2048
	global_load_dwordx4 v[98:101], v[40:41], off offset:3072
	v_xor_b32_e32 v39, 0x80000000, v13
	ds_read_b32 v44, v12
	s_waitcnt vmcnt(3)
	v_pk_mul_f32 v[42:43], v[56:57], v[38:39]
	v_pk_mul_f32 v[52:53], v[54:55], v[14:15] neg_lo:[0,1] neg_hi:[0,1]
	v_mul_f32_e32 v0, v27, v55
	v_mul_f32_e32 v45, v25, v57
	v_pk_mov_b32 v[58:59], v[52:53], v[42:43] op_sel:[1,0]
	v_mov_b32_e32 v53, v43
	v_fmac_f32_e32 v0, v26, v54
	v_fmac_f32_e32 v45, v24, v56
	v_pk_add_f32 v[42:43], v[58:59], v[52:53]
	v_add_f32_e32 v0, v0, v45
	v_add_f32_e32 v42, v42, v43
	s_nop 0
	v_add_f32_dpp v0, v0, v0 quad_perm:[1,0,3,2] row_mask:0xf bank_mask:0xf bound_ctrl:1
	v_add_f32_dpp v42, v42, v42 quad_perm:[1,0,3,2] row_mask:0xf bank_mask:0xf bound_ctrl:1
	s_nop 0
	v_add_f32_dpp v0, v0, v0 quad_perm:[2,3,0,1] row_mask:0xf bank_mask:0xf bound_ctrl:1
	v_add_f32_dpp v42, v42, v42 quad_perm:[2,3,0,1] row_mask:0xf bank_mask:0xf bound_ctrl:1
	s_nop 0
	v_add_f32_dpp v51, v0, v0 row_half_mirror row_mask:0xf bank_mask:0xf bound_ctrl:1
	v_add_f32_dpp v0, v42, v42 row_half_mirror row_mask:0xf bank_mask:0xf bound_ctrl:1
	s_nop 0
	v_mov_b32_dpp v52, v51 row_mirror row_mask:0xf bank_mask:0xf bound_ctrl:1
	v_add_f32_dpp v0, v0, v0 row_mirror row_mask:0xf bank_mask:0xf bound_ctrl:1
	v_pk_mul_f32 v[42:43], v[16:17], v[0:1] op_sel_hi:[1,0]
	v_pk_mul_f32 v[58:59], v[18:19], v[0:1] op_sel_hi:[1,0]
	v_pk_fma_f32 v[42:43], v[22:23], v[56:57], v[42:43]
	v_pk_fma_f32 v[54:55], v[20:21], v[54:55], v[58:59]
	s_waitcnt lgkmcnt(0)
	v_pk_fma_f32 v[56:57], v[8:9], v[44:45], v[42:43] op_sel_hi:[1,0,1]
	v_pk_fma_f32 v[54:55], v[10:11], v[44:45], v[54:55] op_sel_hi:[1,0,1]
	v_lshl_add_u64 v[42:43], v[34:35], 0, s[0:1]
	global_store_dwordx4 v[42:43], v[54:57], off offset:-2048
	s_and_saveexec_b64 s[26:27], s[4:5]
	s_cbranch_execz .LBB0_1035
	v_mov_b32_e32 v45, v0
	v_pk_mul_f32 v[44:45], v[28:29], v[44:45]
	v_add_f32_e32 v0, v51, v52
	v_add_f32_e32 v0, v45, v0
	v_add_f32_e32 v0, v44, v0
	v_cvt_pk_bf16_f32 v0, v0, s0
	global_store_short v[30:31], v0, off
.LBB0_1035:
	s_or_b64 exec, exec, s[26:27]
	ds_read_b32 v44, v12 offset:16
	s_waitcnt vmcnt(3)
	v_pk_mul_f32 v[52:53], v[92:93], v[38:39]
	v_pk_mul_f32 v[58:59], v[90:91], v[14:15] neg_lo:[0,1] neg_hi:[0,1]
	v_mul_f32_e32 v0, v27, v91
	v_mul_f32_e32 v45, v25, v93
	v_pk_mov_b32 v[60:61], v[58:59], v[52:53] op_sel:[1,0]
	v_mov_b32_e32 v59, v53
	v_fmac_f32_e32 v0, v26, v90
	v_fmac_f32_e32 v45, v24, v92
	v_pk_add_f32 v[52:53], v[60:61], v[58:59]
	v_add_f32_e32 v0, v0, v45
	v_add_f32_e32 v45, v52, v53
	s_nop 0
	v_add_f32_dpp v0, v0, v0 quad_perm:[1,0,3,2] row_mask:0xf bank_mask:0xf bound_ctrl:1
	v_add_f32_dpp v45, v45, v45 quad_perm:[1,0,3,2] row_mask:0xf bank_mask:0xf bound_ctrl:1
	s_nop 0
	v_add_f32_dpp v0, v0, v0 quad_perm:[2,3,0,1] row_mask:0xf bank_mask:0xf bound_ctrl:1
	v_add_f32_dpp v45, v45, v45 quad_perm:[2,3,0,1] row_mask:0xf bank_mask:0xf bound_ctrl:1
	s_nop 0
	v_add_f32_dpp v51, v0, v0 row_half_mirror row_mask:0xf bank_mask:0xf bound_ctrl:1
	v_add_f32_dpp v0, v45, v45 row_half_mirror row_mask:0xf bank_mask:0xf bound_ctrl:1
	s_nop 0
	v_mov_b32_dpp v52, v51 row_mirror row_mask:0xf bank_mask:0xf bound_ctrl:1
	v_add_f32_dpp v0, v0, v0 row_mirror row_mask:0xf bank_mask:0xf bound_ctrl:1
	v_pk_mul_f32 v[58:59], v[16:17], v[0:1] op_sel_hi:[1,0]
	v_pk_mul_f32 v[60:61], v[18:19], v[0:1] op_sel_hi:[1,0]
	v_pk_fma_f32 v[56:57], v[22:23], v[92:93], v[58:59]
	v_pk_fma_f32 v[54:55], v[20:21], v[90:91], v[60:61]
	s_waitcnt lgkmcnt(0)
	v_pk_fma_f32 v[56:57], v[8:9], v[44:45], v[56:57] op_sel_hi:[1,0,1]
	v_pk_fma_f32 v[54:55], v[10:11], v[44:45], v[54:55] op_sel_hi:[1,0,1]
	global_store_dwordx4 v[42:43], v[54:57], off offset:-1024
	s_and_saveexec_b64 s[26:27], s[4:5]
	s_cbranch_execz .LBB0_1037
	v_mov_b32_e32 v45, v0
	v_pk_mul_f32 v[44:45], v[28:29], v[44:45]
	v_add_f32_e32 v0, v51, v52
	v_add_f32_e32 v0, v45, v0
	v_add_f32_e32 v0, v44, v0
	v_cvt_pk_bf16_f32 v0, v0, s0
	global_store_short v[36:37], v0, off offset:-8
; __device__ __forceinline__ bf16_t f2bf(float f) { return (bf16_t)(cvt_pk_bf16(f, 0.f) & 0xffffu); }
; __device__ __forceinline__ float dot4(f32x4 a, f32x4 b) { return (a.x * b.x + a.y * b.y) + (a.z * b.z + a.w * b.w); }
; template <int ph>
; __device__ __forceinline__ void run_phase(const Args& args, LAS unsigned char* lds, const int G, const int bx, const bool fin = true) {
;     ...
; #pragma unroll 4
;                 for (int rg = 0; rg < 16; ++rg) {
;                     const int srow = 4 * rg + (lane >> 4);
;                     f32x4 S = *(const f32x4*)(state_rwkv + sbase + srow * 64 + 4 * cgq);
;                     const float vv = V1[320 + srow];
;                     const float sa = red16(dot4(S, nk)), z = red16(dot4(S, wrv));
;                     const float y = z + sa * br + vv * kr;
;                     S = S * w + bv * sa + kp * vv;
;                     *(f32x4*)(out + O_SRWKV + sbase + srow * 64 + 4 * cgq) = S;
;                     if (cgq == 0) Y[row * D + h * 64 + srow] = f2bf(y);
;                 }
.LBB0_1037:
	s_or_b64 exec, exec, s[26:27]
	ds_read_b32 v44, v12 offset:32
	s_waitcnt vmcnt(3)
	v_pk_mul_f32 v[52:53], v[96:97], v[38:39]
	v_pk_mul_f32 v[58:59], v[94:95], v[14:15] neg_lo:[0,1] neg_hi:[0,1]
	v_mul_f32_e32 v0, v27, v95
	v_mul_f32_e32 v45, v25, v97
	v_pk_mov_b32 v[60:61], v[58:59], v[52:53] op_sel:[1,0]
	v_mov_b32_e32 v59, v53
	v_fmac_f32_e32 v0, v26, v94
	v_fmac_f32_e32 v45, v24, v96
	v_pk_add_f32 v[52:53], v[60:61], v[58:59]
	v_add_f32_e32 v0, v0, v45
	v_add_f32_e32 v45, v52, v53
	s_nop 0
	v_add_f32_dpp v0, v0, v0 quad_perm:[1,0,3,2] row_mask:0xf bank_mask:0xf bound_ctrl:1
	v_add_f32_dpp v45, v45, v45 quad_perm:[1,0,3,2] row_mask:0xf bank_mask:0xf bound_ctrl:1
	s_nop 0
	v_add_f32_dpp v0, v0, v0 quad_perm:[2,3,0,1] row_mask:0xf bank_mask:0xf bound_ctrl:1
	v_add_f32_dpp v45, v45, v45 quad_perm:[2,3,0,1] row_mask:0xf bank_mask:0xf bound_ctrl:1
	s_nop 0
	v_add_f32_dpp v51, v0, v0 row_half_mirror row_mask:0xf bank_mask:0xf bound_ctrl:1
	v_add_f32_dpp v0, v45, v45 row_half_mirror row_mask:0xf bank_mask:0xf bound_ctrl:1
	s_nop 0
	v_mov_b32_dpp v52, v51 row_mirror row_mask:0xf bank_mask:0xf bound_ctrl:1
	v_add_f32_dpp v0, v0, v0 row_mirror row_mask:0xf bank_mask:0xf bound_ctrl:1
	v_pk_mul_f32 v[58:59], v[16:17], v[0:1] op_sel_hi:[1,0]
	v_pk_mul_f32 v[60:61], v[18:19], v[0:1] op_sel_hi:[1,0]
	v_pk_fma_f32 v[56:57], v[22:23], v[96:97], v[58:59]
	v_pk_fma_f32 v[54:55], v[20:21], v[94:95], v[60:61]
	s_waitcnt lgkmcnt(0)
	v_pk_fma_f32 v[56:57], v[8:9], v[44:45], v[56:57] op_sel_hi:[1,0,1]
	v_pk_fma_f32 v[54:55], v[10:11], v[44:45], v[54:55] op_sel_hi:[1,0,1]
	global_store_dwordx4 v[42:43], v[54:57], off
	s_and_saveexec_b64 s[26:27], s[4:5]
	s_cbranch_execz .LBB0_1039
	v_mov_b32_e32 v45, v0
	v_pk_mul_f32 v[44:45], v[28:29], v[44:45]
	v_add_f32_e32 v0, v51, v52
	v_add_f32_e32 v0, v45, v0
	v_add_f32_e32 v0, v44, v0
	v_cvt_pk_bf16_f32 v0, v0, s0
	global_store_short v[36:37], v0, off
.LBB0_1039:
	s_or_b64 exec, exec, s[26:27]
	ds_read_b32 v40, v12 offset:48
	s_waitcnt vmcnt(3)
	v_pk_mul_f32 v[44:45], v[100:101], v[38:39]
	v_pk_mul_f32 v[56:57], v[98:99], v[14:15] neg_lo:[0,1] neg_hi:[0,1]
	v_mul_f32_e32 v0, v27, v99
	v_mul_f32_e32 v39, v25, v101
	v_pk_mov_b32 v[58:59], v[56:57], v[44:45] op_sel:[1,0]
	v_mov_b32_e32 v57, v45
	v_fmac_f32_e32 v0, v26, v98
	v_fmac_f32_e32 v39, v24, v100
	v_pk_add_f32 v[44:45], v[58:59], v[56:57]
	v_add_f32_e32 v0, v0, v39
	v_add_f32_e32 v39, v44, v45
	s_nop 0
	v_add_f32_dpp v0, v0, v0 quad_perm:[1,0,3,2] row_mask:0xf bank_mask:0xf bound_ctrl:1
	v_add_f32_dpp v39, v39, v39 quad_perm:[1,0,3,2] row_mask:0xf bank_mask:0xf bound_ctrl:1
	s_nop 0
	v_add_f32_dpp v0, v0, v0 quad_perm:[2,3,0,1] row_mask:0xf bank_mask:0xf bound_ctrl:1
	v_add_f32_dpp v41, v39, v39 quad_perm:[2,3,0,1] row_mask:0xf bank_mask:0xf bound_ctrl:1
	s_nop 0
	v_add_f32_dpp v39, v0, v0 row_half_mirror row_mask:0xf bank_mask:0xf bound_ctrl:1
	v_add_f32_dpp v0, v41, v41 row_half_mirror row_mask:0xf bank_mask:0xf bound_ctrl:1
	s_nop 0
	v_mov_b32_dpp v44, v39 row_mirror row_mask:0xf bank_mask:0xf bound_ctrl:1
	v_add_f32_dpp v0, v0, v0 row_mirror row_mask:0xf bank_mask:0xf bound_ctrl:1
	v_pk_mul_f32 v[56:57], v[16:17], v[0:1] op_sel_hi:[1,0]
	v_pk_mul_f32 v[58:59], v[18:19], v[0:1] op_sel_hi:[1,0]
	v_pk_fma_f32 v[54:55], v[22:23], v[100:101], v[56:57]
	v_pk_fma_f32 v[52:53], v[20:21], v[98:99], v[58:59]
	s_waitcnt lgkmcnt(0)
	v_pk_fma_f32 v[54:55], v[8:9], v[40:41], v[54:55] op_sel_hi:[1,0,1]
	v_pk_fma_f32 v[52:53], v[10:11], v[40:41], v[52:53] op_sel_hi:[1,0,1]
	global_store_dwordx4 v[42:43], v[52:55], off offset:1024
	s_and_saveexec_b64 s[26:27], s[4:5]
	s_cbranch_execz .LBB0_1032
	v_mov_b32_e32 v41, v0
	v_pk_mul_f32 v[40:41], v[28:29], v[40:41]
	v_add_f32_e32 v0, v39, v44
	v_add_f32_e32 v0, v41, v0
	v_add_f32_e32 v0, v40, v0
	v_cvt_pk_bf16_f32 v0, v0, s0
	global_store_short v[36:37], v0, off offset:8
	s_branch .LBB0_1032
